# ffn_in: next tile's first eight LDS-DMA loads issued at start of the current tile's epilogue
# speedup vs baseline: 1.0693x; 1.0027x over previous
.LBB0_789:
	s_andn2_b64 vcc, exec, s[0:1]
	s_cbranch_vccnz .LBB0_798
	s_waitcnt lgkmcnt(0)
	s_add_u32 s31, s48, 0xdca0000
	v_readlane_b32 s0, v255, 6
	s_addc_u32 s40, s49, 0
	s_mul_i32 s41, s0, 0xb00000
	s_add_u32 s0, s48, s41
	s_addc_u32 s1, s49, 0
	s_add_u32 s42, s0, 0x1a04000
	s_addc_u32 s43, s1, 0
	s_add_u32 s0, s48, 0x10ca0000
	s_addc_u32 s1, s49, 0
	s_waitcnt vmcnt(0)
	s_mov_b64 s[56:57], 0
	s_branch .LBB0_792
.LBB0_791:
	s_mov_b64 s[56:57], 0
	s_cmpk_gt_i32 s30, 0x1bf
	s_cbranch_scc1 .Lpf_skip
	v_and_b32_e32 v200, 63, v156
	v_lshlrev_b32_e32 v200, 4, v200
	v_bfe_u32 v201, v200, 9, 1
	v_lshlrev_b32_e32 v201, 5, v201
	v_xor_b32_e32 v200, v200, v201
	v_lshrrev_b32_e32 v201, 6, v156
	v_lshrrev_b32_e32 v202, 1, v201
	v_lshlrev_b32_e32 v202, 4, v202
	v_lshrrev_b32_e32 v203, 6, v200
	v_add_u32_e32 v202, v202, v203
	v_and_b32_e32 v203, 1, v201
	v_lshlrev_b32_e32 v203, 5, v203
	v_bfe_u32 v204, v200, 1, 5
	v_add_u32_e32 v203, v203, v204
	v_lshlrev_b32_e32 v202, 11, v202
	v_lshl_add_u32 v200, v203, 1, v202
	v_readfirstlane_b32 s56, v201
	s_lshl_b32 s56, s56, 10
	s_add_i32 s57, s30, 0x100
	s_ashr_i32 s57, s57, 5
	s_lshl_b32 s57, s57, 19
	s_add_u32 s98, s42, s57
	s_addc_u32 s99, s43, 0
	s_and_b32 s57, s30, 31
	s_lshl_b32 s57, s57, 19
	s_add_u32 s58, s31, s57
	s_addc_u32 s59, s40, 0
	s_add_i32 m0, s56, 0x10000
	s_nop 0
	global_load_lds_dwordx4 v200, s[98:99]
	s_add_u32 s98, s98, 0x20000
	s_addc_u32 s99, s99, 0
	s_add_i32 m0, s56, 0x12000
	s_nop 0
	global_load_lds_dwordx4 v200, s[98:99]
	s_add_i32 m0, s56, 0x0
	s_nop 0
	global_load_lds_dwordx4 v200, s[58:59]
	s_add_u32 s58, s58, 0x20000
	s_addc_u32 s59, s59, 0
	s_add_i32 m0, s56, 0x2000
	s_nop 0
	global_load_lds_dwordx4 v200, s[58:59]
	s_add_u32 s98, s98, 0x20000
	s_addc_u32 s99, s99, 0
	s_add_i32 m0, s56, 0x14000
	s_nop 0
	global_load_lds_dwordx4 v200, s[98:99]
	s_add_u32 s98, s98, 0x20000
	s_addc_u32 s99, s99, 0
	s_add_i32 m0, s56, 0x16000
	s_nop 0
	global_load_lds_dwordx4 v200, s[98:99]
	s_add_u32 s58, s58, 0x20000
	s_addc_u32 s59, s59, 0
	s_add_i32 m0, s56, 0x4000
	s_nop 0
	global_load_lds_dwordx4 v200, s[58:59]
	s_add_u32 s58, s58, 0x20000
	s_addc_u32 s59, s59, 0
	s_add_i32 m0, s56, 0x6000
	s_nop 0
	global_load_lds_dwordx4 v200, s[58:59]
	s_mov_b64 s[56:57], -1

.LBB0_792:
	s_mov_b64 vcc, s[56:57]
	v_mov_b32_e32 v13, v156
	s_and_b32 s33, s30, 31
	v_ashrrev_i32_e32 v0, 31, v13
	v_lshrrev_b32_e32 v0, 26, v0
	v_add_u32_e32 v0, v13, v0
	v_ashrrev_i32_e32 v4, 6, v0
	v_bfe_i32 v0, v13, 27, 1
	v_lshlrev_b32_e32 v5, 4, v13
	v_lshrrev_b32_e32 v0, 22, v0
	v_add_u32_e32 v0, v5, v0
	v_and_b32_e32 v0, 0xfffffc00, v0
	v_sub_u32_e32 v0, v5, v0
	v_lshrrev_b32_e32 v1, 4, v0
	v_bitop3_b32 v1, v1, v0, 32 bitop3:0x6c
	v_ashrrev_i32_e32 v0, 31, v0
	v_lshrrev_b32_e32 v0, 26, v0
	v_lshlrev_b32_e32 v2, 3, v4
	v_add_u32_e32 v0, v1, v0
	v_and_b32_e32 v2, 0x3ffff0, v2
	v_ashrrev_i32_e32 v6, 6, v0
	v_add_u32_e32 v0, v6, v2
	v_lshlrev_b32_e32 v2, 5, v4
	v_and_b32_e32 v7, 32, v2
	v_mul_i32_i24_e32 v2, 64, v6
	v_sub_u32_e32 v1, v1, v2
	v_ashrrev_i16_sdwa v8, v161, sext(v1) dst_sel:DWORD dst_unused:UNUSED_PAD src0_sel:DWORD src1_sel:BYTE_0
	v_lshl_or_b32 v0, v0, 10, v7
	v_add_u32_sdwa v144, v0, sext(v8) dst_sel:DWORD dst_unused:UNUSED_PAD src0_sel:DWORD src1_sel:WORD_0
	v_add_u32_e32 v0, 0x2000, v5
	v_ashrrev_i32_e32 v1, 31, v0
	v_lshrrev_b32_e32 v1, 22, v1
	v_add_u32_e32 v1, v0, v1
	v_ashrrev_i32_e32 v9, 10, v1
	v_mul_i32_i24_e32 v1, 0x400, v9
	v_sub_u32_e32 v0, v0, v1
	v_lshrrev_b32_e32 v1, 4, v0
	s_ashr_i32 s4, s30, 5
	s_lshl_b32 s84, s33, 19
	v_bitop3_b32 v0, v1, v0, 32 bitop3:0x6c
	s_add_u32 s28, s31, s84
	v_ashrrev_i32_e32 v2, 31, v0
	s_addc_u32 s29, s40, 0
	s_ashr_i32 s5, s4, 31
	v_lshrrev_b32_e32 v2, 26, v2
	s_lshl_b64 s[24:25], s[4:5], 19
	v_lshlrev_b32_e32 v1, 3, v9
	v_add_u32_e32 v2, v0, v2
	s_add_u32 s50, s42, s24
	v_and_b32_e32 v1, 0x3ffff0, v1
	v_ashrrev_i32_e32 v10, 6, v2
	v_lshlrev_b32_e32 v3, 5, v9
	v_and_b32_e32 v2, 0xc0, v2
	s_addc_u32 s51, s43, s25
	v_add_u32_e32 v1, v10, v1
	v_and_b32_e32 v11, 32, v3
	v_sub_u32_e32 v0, v0, v2
	s_add_i32 s44, 0, 0x10000
	v_ashrrev_i16_sdwa v12, v161, sext(v0) dst_sel:DWORD dst_unused:UNUSED_PAD src0_sel:DWORD src1_sel:BYTE_0
	v_lshl_or_b32 v0, v1, 10, v11
	v_add_u32_e32 v142, s44, v5
	v_add_u32_sdwa v2, v0, sext(v12) dst_sel:DWORD dst_unused:UNUSED_PAD src0_sel:DWORD src1_sel:WORD_0
	v_lshlrev_b64 v[14:15], 1, v[144:145]
	v_readfirstlane_b32 s45, v142
	v_mov_b32_e32 v3, v145
	v_add_u32_e32 v143, 0x2000, v142
	v_readfirstlane_b32 s5, v13
	v_lshl_add_u64 v[0:1], s[50:51], 0, v[14:15]
	s_mov_b32 m0, s45
	v_lshlrev_b64 v[16:17], 1, v[2:3]
	v_readfirstlane_b32 s45, v143
	v_add_u32_e32 v147, 0, v5
	s_ashr_i32 s46, s5, 8
	s_barrier
	s_cbranch_vccnz .Lpf_h1
	global_load_lds_dwordx4 v[0:1], off
.Lpf_h1:
	v_lshl_add_u64 v[2:3], s[50:51], 0, v[16:17]
	s_mov_b32 m0, s45
	v_readfirstlane_b32 s45, v147
	v_add_u32_e32 v148, 0x2000, v147
	s_cbranch_vccnz .Lpf_h2
	global_load_lds_dwordx4 v[2:3], off
.Lpf_h2:
	v_lshl_add_u64 v[130:131], s[28:29], 0, v[14:15]
	s_mov_b32 m0, s45
	v_readfirstlane_b32 s45, v148
	s_add_u32 s50, s50, 0x40000
	s_cbranch_vccnz .Lpf_h3
	global_load_lds_dwordx4 v[130:131], off
.Lpf_h3:
	s_mov_b32 m0, s45
	s_addc_u32 s51, s51, 0
	s_add_i32 s45, 0, 0x14000
	v_add_u32_e32 v149, s45, v5
	v_lshl_add_u64 v[128:129], s[28:29], 0, v[16:17]
	v_readfirstlane_b32 s47, v149
	v_add_u32_e32 v150, 0x2000, v149
	s_cbranch_vccnz .Lpf_h4
	global_load_lds_dwordx4 v[128:129], off
.Lpf_h4:
	v_lshl_add_u64 v[18:19], s[50:51], 0, v[14:15]
	s_mov_b32 m0, s47
	v_readfirstlane_b32 s47, v150
	s_add_u32 s28, s28, 0x40000
	v_add_u32_e32 v151, 0x4000, v147
	s_cbranch_vccnz .Lpf_h5
	global_load_lds_dwordx4 v[18:19], off
.Lpf_h5:
	v_lshl_add_u64 v[18:19], s[50:51], 0, v[16:17]
	s_mov_b32 m0, s47
	s_addc_u32 s29, s29, 0
	v_readfirstlane_b32 s47, v151
	s_cbranch_vccnz .Lpf_h6
	global_load_lds_dwordx4 v[18:19], off
.Lpf_h6:
	v_lshl_add_u64 v[14:15], s[28:29], 0, v[14:15]
	s_mov_b32 m0, s47
	v_add_u32_e32 v152, 0x6000, v147
	s_cbranch_vccnz .Lpf_h7
	global_load_lds_dwordx4 v[14:15], off
.Lpf_h7:
	v_lshl_add_u64 v[14:15], s[28:29], 0, v[16:17]
	v_readfirstlane_b32 s28, v152
	s_mov_b32 m0, s28
	s_cmp_lg_u32 s46, 1
	s_cbranch_vccnz .Lpf_h8
	global_load_lds_dwordx4 v[14:15], off
.Lpf_h8:
	s_cbranch_scc1 .LBB0_794
	s_barrier
.LBB0_794:
	v_lshrrev_b32_e32 v15, 1, v13
	v_and_b32_e32 v15, 24, v15
	v_and_b32_e32 v14, 15, v13
	v_lshlrev_b32_e32 v144, 1, v15
	v_lshlrev_b32_e32 v13, 2, v13
	v_lshl_or_b32 v140, s46, 6, v14
	v_lshl_or_b32 v14, v14, 6, v144
	s_lshr_b32 s28, s5, 1
	v_and_b32_e32 v13, 32, v13
	s_lshl_b32 s29, s46, 13
	s_and_b32 s28, s28, 0x60
	v_bitop3_b32 v16, v14, s29, v13 bitop3:0xde
	s_add_i32 s29, 0, 0x18000
	s_lshl_b32 s46, s28, 7
	v_add_u32_e32 v154, s29, v5
	v_bitop3_b32 v153, v14, s46, v13 bitop3:0xde
	v_readfirstlane_b32 s46, v154
	v_add_u32_e32 v155, 0x2000, v154
	v_lshl_add_u64 v[14:15], v[0:1], 0, s[86:87]
	s_mov_b32 m0, s46
	v_readfirstlane_b32 s46, v155
	v_add_u32_e32 v173, 0x8000, v147
	s_cbranch_vccnz .Lpf_w1
	s_waitcnt vmcnt(4)
	s_branch .Lpf_w2
.Lpf_w1:
	s_waitcnt vmcnt(12)
.Lpf_w2:
	s_barrier
	global_load_lds_dwordx4 v[14:15], off
	v_lshl_add_u64 v[14:15], v[2:3], 0, s[86:87]
	s_mov_b32 m0, s46
	v_readfirstlane_b32 s46, v173
	v_add_u32_e32 v174, 0xa000, v147
	global_load_lds_dwordx4 v[14:15], off
	v_lshl_add_u64 v[14:15], v[130:131], 0, s[86:87]
	s_mov_b32 m0, s46
	v_readfirstlane_b32 s46, v174
	v_add_u32_e32 v175, s62, v5
	global_load_lds_dwordx4 v[14:15], off
	v_lshl_add_u64 v[14:15], v[128:129], 0, s[86:87]
	s_mov_b32 m0, s46
	s_mov_b64 s[50:51], 0x40080
	v_readfirstlane_b32 s46, v175
	v_add_u32_e32 v176, 0x2000, v175
	global_load_lds_dwordx4 v[14:15], off
	v_lshl_add_u64 v[0:1], v[0:1], 0, s[50:51]
	s_mov_b32 m0, s46
	v_readfirstlane_b32 s46, v176
	global_load_lds_dwordx4 v[0:1], off
	v_lshl_add_u64 v[0:1], v[2:3], 0, s[50:51]
	s_mov_b32 m0, s46
	v_lshlrev_b32_e32 v2, 13, v9
	global_load_lds_dwordx4 v[0:1], off
	v_lshlrev_b32_e32 v0, 13, v4
	v_and_b32_e32 v0, 0xffffc000, v0
	v_lshl_add_u32 v0, v6, 10, v0
	v_and_b32_e32 v2, 0xffffc000, v2
	v_or_b32_e32 v0, v0, v7
	v_lshl_add_u32 v2, v10, 10, v2
	v_add_u32_sdwa v0, v0, sext(v8) dst_sel:DWORD dst_unused:UNUSED_PAD src0_sel:DWORD src1_sel:WORD_0
	v_mov_b32_e32 v1, v145
	v_or_b32_e32 v2, v2, v11
	s_add_u32 s24, s41, s24
	s_waitcnt vmcnt(6)
	v_lshlrev_b64 v[0:1], 1, v[0:1]
	v_add_u32_sdwa v2, v2, sext(v12) dst_sel:DWORD dst_unused:UNUSED_PAD src0_sel:DWORD src1_sel:WORD_0
	v_mov_b32_e32 v3, v145
	s_addc_u32 s25, 0, s25
	v_lshl_add_u64 v[132:133], s[84:85], 0, v[0:1]
	v_lshlrev_b64 v[2:3], 1, v[2:3]
	v_lshl_add_u64 v[136:137], s[24:25], 0, v[0:1]
	v_mov_b32_e32 v0, 0
	v_lshl_add_u64 v[134:135], s[84:85], 0, v[2:3]
	v_lshl_add_u64 v[138:139], s[24:25], 0, v[2:3]
	s_mov_b32 s24, -2
	v_add_u32_e32 v141, 0, v16
	v_mov_b32_e32 v1, v0
	v_mov_b32_e32 v2, v0
	v_mov_b32_e32 v3, v0
	v_mov_b32_e32 v4, v0
	v_mov_b32_e32 v5, v0
	v_mov_b32_e32 v6, v0
	v_mov_b32_e32 v7, v0
	v_mov_b32_e32 v8, v0
	v_mov_b32_e32 v9, v0
	v_mov_b32_e32 v10, v0
	v_mov_b32_e32 v11, v0
	v_mov_b32_e32 v12, v0
	v_mov_b32_e32 v13, v0
	v_mov_b32_e32 v14, v0
	v_mov_b32_e32 v15, v0
	v_mov_b32_e32 v16, v0
	v_mov_b32_e32 v17, v0
	v_mov_b32_e32 v18, v0
	v_mov_b32_e32 v19, v0
	v_mov_b32_e32 v20, v0
	v_mov_b32_e32 v21, v0
	v_mov_b32_e32 v22, v0
	v_mov_b32_e32 v23, v0
	v_mov_b32_e32 v24, v0
	v_mov_b32_e32 v25, v0
	v_mov_b32_e32 v26, v0
	v_mov_b32_e32 v27, v0
	v_mov_b32_e32 v28, v0
	v_mov_b32_e32 v29, v0
	v_mov_b32_e32 v30, v0
	v_mov_b32_e32 v31, v0
	v_mov_b32_e32 v32, v0
	v_mov_b32_e32 v33, v0
	v_mov_b32_e32 v34, v0
	v_mov_b32_e32 v35, v0
	v_mov_b32_e32 v36, v0
	v_mov_b32_e32 v37, v0
	v_mov_b32_e32 v38, v0
	v_mov_b32_e32 v39, v0
	v_mov_b32_e32 v40, v0
	v_mov_b32_e32 v41, v0
	v_mov_b32_e32 v42, v0
	v_mov_b32_e32 v43, v0
	v_mov_b32_e32 v44, v0
	v_mov_b32_e32 v45, v0
	v_mov_b32_e32 v46, v0
	v_mov_b32_e32 v47, v0
	v_mov_b32_e32 v48, v0
	v_mov_b32_e32 v49, v0
	v_mov_b32_e32 v50, v0
	v_mov_b32_e32 v51, v0
	v_mov_b32_e32 v52, v0
	v_mov_b32_e32 v53, v0
	v_mov_b32_e32 v54, v0
	v_mov_b32_e32 v55, v0
	v_mov_b32_e32 v56, v0
	v_mov_b32_e32 v57, v0
	v_mov_b32_e32 v58, v0
	v_mov_b32_e32 v59, v0
	v_mov_b32_e32 v60, v0
	v_mov_b32_e32 v61, v0
	v_mov_b32_e32 v62, v0
	v_mov_b32_e32 v63, v0
	v_mov_b32_e32 v64, v0
	v_mov_b32_e32 v65, v0
	v_mov_b32_e32 v66, v0
	v_mov_b32_e32 v67, v0
	v_mov_b32_e32 v68, v0
	v_mov_b32_e32 v69, v0
	v_mov_b32_e32 v70, v0
	v_mov_b32_e32 v71, v0
	v_mov_b32_e32 v80, v0
	v_mov_b32_e32 v81, v0
	v_mov_b32_e32 v82, v0
	v_mov_b32_e32 v83, v0
	v_mov_b32_e32 v84, v0
	v_mov_b32_e32 v85, v0
	v_mov_b32_e32 v86, v0
	v_mov_b32_e32 v87, v0
	v_mov_b32_e32 v88, v0
	v_mov_b32_e32 v89, v0
	v_mov_b32_e32 v90, v0
	v_mov_b32_e32 v91, v0
	v_mov_b32_e32 v92, v0
	v_mov_b32_e32 v93, v0
	v_mov_b32_e32 v94, v0
	v_mov_b32_e32 v95, v0
	v_mov_b32_e32 v96, v0
	v_mov_b32_e32 v97, v0
	v_mov_b32_e32 v98, v0
	v_mov_b32_e32 v99, v0
	v_mov_b32_e32 v100, v0
	v_mov_b32_e32 v101, v0
	v_mov_b32_e32 v102, v0
	v_mov_b32_e32 v103, v0
	v_mov_b32_e32 v104, v0
	v_mov_b32_e32 v105, v0
	v_mov_b32_e32 v106, v0
	v_mov_b32_e32 v107, v0
	v_mov_b32_e32 v108, v0
	v_mov_b32_e32 v109, v0
	v_mov_b32_e32 v110, v0
	v_mov_b32_e32 v111, v0
	v_mov_b32_e32 v112, v0
	v_mov_b32_e32 v113, v0
	v_mov_b32_e32 v114, v0
	v_mov_b32_e32 v115, v0
	v_mov_b32_e32 v116, v0
	v_mov_b32_e32 v117, v0
	v_mov_b32_e32 v118, v0
	v_mov_b32_e32 v119, v0
	v_mov_b32_e32 v120, v0
	v_mov_b32_e32 v121, v0
	v_mov_b32_e32 v122, v0
	v_mov_b32_e32 v123, v0
	v_mov_b32_e32 v124, v0
	v_mov_b32_e32 v125, v0
	v_mov_b32_e32 v126, v0
	v_mov_b32_e32 v127, v0
	v_mov_b32_e32 v72, v0
	v_mov_b32_e32 v73, v0
	v_mov_b32_e32 v74, v0
	v_mov_b32_e32 v75, v0
	v_mov_b32_e32 v76, v0
	v_mov_b32_e32 v77, v0
	v_mov_b32_e32 v78, v0
	v_mov_b32_e32 v79, v0
	s_barrier
